# GEMM units: accumulator zeroing with 64-bit moves (64 instead of 128 VALU ops per unit start)
# speedup vs baseline: 1.0485x; 1.0017x over previous
.Lwpf_skip:
	s_ashr_i32 s21, s20, 31
	s_lshl_b64 s[22:23], s[20:21], 19
	s_add_u32 s22, s80, s22
	s_addc_u32 s23, s81, s23
	s_and_b64 s[24:25], s[2:3], exec
	s_cselect_b32 s5, s23, s29
	s_cselect_b32 s21, s22, s28
	s_ashr_i32 s19, s18, 31
	s_lshl_b64 s[24:25], s[18:19], 18
	s_add_u32 s24, s33, s24
	s_addc_u32 s25, s36, s25
	s_and_b64 s[34:35], s[2:3], exec
	s_cselect_b32 s19, s25, s31
	s_cselect_b32 s27, s24, s30
	s_add_u32 s28, s28, 0x40080
	s_addc_u32 s29, s29, 0
	s_add_u32 s60, s30, 0x100
	v_mov_b32_e32 v6, 0
	s_addc_u32 s61, s31, 0
	s_mov_b32 s62, -2
	v_mov_b32_e32 v7, v6
	v_mov_b64_e32 v[8:9], 0
	v_mov_b64_e32 v[10:11], 0
	v_mov_b64_e32 v[12:13], 0
	v_mov_b64_e32 v[22:23], 0
	v_mov_b64_e32 v[24:25], 0
	v_mov_b64_e32 v[26:27], 0
	v_mov_b64_e32 v[28:29], 0
	v_mov_b64_e32 v[38:39], 0
	v_mov_b64_e32 v[40:41], 0
	v_mov_b64_e32 v[42:43], 0
	v_mov_b64_e32 v[44:45], 0
	v_mov_b64_e32 v[54:55], 0
	v_mov_b64_e32 v[56:57], 0
	v_mov_b64_e32 v[58:59], 0
	v_mov_b64_e32 v[60:61], 0
	v_mov_b64_e32 v[14:15], 0
	v_mov_b64_e32 v[16:17], 0
	v_mov_b64_e32 v[18:19], 0
	v_mov_b64_e32 v[20:21], 0
	v_mov_b64_e32 v[30:31], 0
	v_mov_b64_e32 v[32:33], 0
	v_mov_b64_e32 v[34:35], 0
	v_mov_b64_e32 v[36:37], 0
	v_mov_b64_e32 v[46:47], 0
	v_mov_b64_e32 v[48:49], 0
	v_mov_b64_e32 v[50:51], 0
	v_mov_b64_e32 v[52:53], 0
	v_mov_b64_e32 v[62:63], 0
	v_mov_b64_e32 v[64:65], 0
	v_mov_b64_e32 v[66:67], 0
	v_mov_b64_e32 v[68:69], 0
	v_mov_b64_e32 v[70:71], 0
	v_mov_b64_e32 v[72:73], 0
	v_mov_b64_e32 v[74:75], 0
	v_mov_b64_e32 v[76:77], 0
	v_mov_b64_e32 v[86:87], 0
	v_mov_b64_e32 v[88:89], 0
	v_mov_b64_e32 v[90:91], 0
	v_mov_b64_e32 v[92:93], 0
	v_mov_b64_e32 v[102:103], 0
	v_mov_b64_e32 v[104:105], 0
	v_mov_b64_e32 v[106:107], 0
	v_mov_b64_e32 v[108:109], 0
	v_mov_b64_e32 v[118:119], 0
	v_mov_b64_e32 v[120:121], 0
	v_mov_b64_e32 v[122:123], 0
	v_mov_b64_e32 v[124:125], 0
	v_mov_b64_e32 v[78:79], 0
	v_mov_b64_e32 v[80:81], 0
	v_mov_b64_e32 v[82:83], 0
	v_mov_b64_e32 v[84:85], 0
	v_mov_b64_e32 v[94:95], 0
	v_mov_b64_e32 v[96:97], 0
	v_mov_b64_e32 v[98:99], 0
	v_mov_b64_e32 v[100:101], 0
	v_mov_b64_e32 v[110:111], 0
	v_mov_b64_e32 v[112:113], 0
	v_mov_b64_e32 v[114:115], 0
	v_mov_b64_e32 v[116:117], 0
	v_mov_b64_e32 v[126:127], 0
	v_mov_b64_e32 v[128:129], 0
	v_mov_b64_e32 v[130:131], 0
	v_mov_b64_e32 v[132:133], 0

.LBB0_204:
	s_ashr_i32 s19, s18, 31
	s_lshl_b64 s[20:21], s[18:19], 19
	s_add_u32 s20, s80, s20
	s_addc_u32 s21, s81, s21
	s_and_b64 s[22:23], s[4:5], exec
	s_cselect_b32 s7, s21, s27
	s_cselect_b32 s19, s20, s26
	s_ashr_i32 s17, s16, 31
	s_lshl_b64 s[22:23], s[16:17], 19
	s_add_u32 s22, s33, s22
	s_addc_u32 s23, s34, s23
	s_and_b64 s[30:31], s[4:5], exec
	s_cselect_b32 s17, s23, s29
	s_cselect_b32 s25, s22, s28
	s_add_u32 s26, s26, 0x40080
	s_addc_u32 s27, s27, 0
	s_add_u32 s48, s28, 0x100
	v_mov_b32_e32 v6, 0
	s_addc_u32 s58, s29, 0
	s_mov_b32 s59, -2
	v_mov_b32_e32 v7, v6
	v_mov_b64_e32 v[8:9], 0
	v_mov_b64_e32 v[10:11], 0
	v_mov_b64_e32 v[12:13], 0
	v_mov_b64_e32 v[22:23], 0
	v_mov_b64_e32 v[24:25], 0
	v_mov_b64_e32 v[26:27], 0
	v_mov_b64_e32 v[28:29], 0
	v_mov_b64_e32 v[38:39], 0
	v_mov_b64_e32 v[40:41], 0
	v_mov_b64_e32 v[42:43], 0
	v_mov_b64_e32 v[44:45], 0
	v_mov_b64_e32 v[70:71], 0
	v_mov_b64_e32 v[72:73], 0
	v_mov_b64_e32 v[74:75], 0
	v_mov_b64_e32 v[76:77], 0
	v_mov_b64_e32 v[14:15], 0
	v_mov_b64_e32 v[16:17], 0
	v_mov_b64_e32 v[18:19], 0
	v_mov_b64_e32 v[20:21], 0
	v_mov_b64_e32 v[30:31], 0
	v_mov_b64_e32 v[32:33], 0
	v_mov_b64_e32 v[34:35], 0
	v_mov_b64_e32 v[36:37], 0
	v_mov_b64_e32 v[62:63], 0
	v_mov_b64_e32 v[64:65], 0
	v_mov_b64_e32 v[66:67], 0
	v_mov_b64_e32 v[68:69], 0
	v_mov_b64_e32 v[78:79], 0
	v_mov_b64_e32 v[80:81], 0
	v_mov_b64_e32 v[82:83], 0
	v_mov_b64_e32 v[84:85], 0
	v_mov_b64_e32 v[86:87], 0
	v_mov_b64_e32 v[88:89], 0
	v_mov_b64_e32 v[90:91], 0
	v_mov_b64_e32 v[92:93], 0
	v_mov_b64_e32 v[102:103], 0
	v_mov_b64_e32 v[104:105], 0
	v_mov_b64_e32 v[106:107], 0
	v_mov_b64_e32 v[108:109], 0
	v_mov_b64_e32 v[118:119], 0
	v_mov_b64_e32 v[120:121], 0
	v_mov_b64_e32 v[122:123], 0
	v_mov_b64_e32 v[124:125], 0
	v_mov_b64_e32 v[134:135], 0
	v_mov_b64_e32 v[136:137], 0
	v_mov_b64_e32 v[138:139], 0
	v_mov_b64_e32 v[140:141], 0
	v_mov_b64_e32 v[94:95], 0
	v_mov_b64_e32 v[96:97], 0
	v_mov_b64_e32 v[98:99], 0
	v_mov_b64_e32 v[100:101], 0
	v_mov_b64_e32 v[110:111], 0
	v_mov_b64_e32 v[112:113], 0
	v_mov_b64_e32 v[114:115], 0
	v_mov_b64_e32 v[116:117], 0
	v_mov_b64_e32 v[126:127], 0
	v_mov_b64_e32 v[128:129], 0
	v_mov_b64_e32 v[130:131], 0
	v_mov_b64_e32 v[132:133], 0
	v_mov_b64_e32 v[142:143], 0
	v_mov_b64_e32 v[144:145], 0
	v_mov_b64_e32 v[146:147], 0
	v_mov_b64_e32 v[148:149], 0

.LBB0_299:
	s_cmp_lg_u32 s78, 0
	s_cselect_b64 s[34:35], -1, 0
	s_cmp_eq_u32 s78, 0
	s_cselect_b32 s25, s41, s78
	s_cmp_lt_i32 s25, 1
	s_cbranch_scc1 .LBB0_311
	s_add_i32 s31, s25, -2
	s_add_u32 s36, s36, 0x80
	s_addc_u32 s37, s37, 0
	s_add_u32 s78, s38, 0x100
	v_mov_b32_e32 v6, 0
	s_addc_u32 s79, s39, 0
	s_mov_b32 s38, 0
	v_mov_b32_e32 v7, v6
	v_mov_b64_e32 v[8:9], 0
	v_mov_b64_e32 v[10:11], 0
	v_mov_b64_e32 v[12:13], 0
	v_mov_b64_e32 v[22:23], 0
	v_mov_b64_e32 v[24:25], 0
	v_mov_b64_e32 v[26:27], 0
	v_mov_b64_e32 v[28:29], 0
	v_mov_b64_e32 v[38:39], 0
	v_mov_b64_e32 v[40:41], 0
	v_mov_b64_e32 v[42:43], 0
	v_mov_b64_e32 v[44:45], 0
	v_mov_b64_e32 v[54:55], 0
	v_mov_b64_e32 v[56:57], 0
	v_mov_b64_e32 v[58:59], 0
	v_mov_b64_e32 v[60:61], 0
	v_mov_b64_e32 v[14:15], 0
	v_mov_b64_e32 v[16:17], 0
	v_mov_b64_e32 v[18:19], 0
	v_mov_b64_e32 v[20:21], 0
	v_mov_b64_e32 v[30:31], 0
	v_mov_b64_e32 v[32:33], 0
	v_mov_b64_e32 v[34:35], 0
	v_mov_b64_e32 v[36:37], 0
	v_mov_b64_e32 v[46:47], 0
	v_mov_b64_e32 v[48:49], 0
	v_mov_b64_e32 v[50:51], 0
	v_mov_b64_e32 v[52:53], 0
	v_mov_b64_e32 v[62:63], 0
	v_mov_b64_e32 v[64:65], 0
	v_mov_b64_e32 v[66:67], 0
	v_mov_b64_e32 v[68:69], 0
	v_mov_b64_e32 v[70:71], 0
	v_mov_b64_e32 v[72:73], 0
	v_mov_b64_e32 v[74:75], 0
	v_mov_b64_e32 v[76:77], 0
	v_mov_b64_e32 v[86:87], 0
	v_mov_b64_e32 v[88:89], 0
	v_mov_b64_e32 v[90:91], 0
	v_mov_b64_e32 v[92:93], 0
	v_mov_b64_e32 v[102:103], 0
	v_mov_b64_e32 v[104:105], 0
	v_mov_b64_e32 v[106:107], 0
	v_mov_b64_e32 v[108:109], 0
	v_mov_b64_e32 v[118:119], 0
	v_mov_b64_e32 v[120:121], 0
	v_mov_b64_e32 v[122:123], 0
	v_mov_b64_e32 v[124:125], 0
	v_mov_b64_e32 v[78:79], 0
	v_mov_b64_e32 v[80:81], 0
	v_mov_b64_e32 v[82:83], 0
	v_mov_b64_e32 v[84:85], 0
	v_mov_b64_e32 v[94:95], 0
	v_mov_b64_e32 v[96:97], 0
	v_mov_b64_e32 v[98:99], 0
	v_mov_b64_e32 v[100:101], 0
	v_mov_b64_e32 v[110:111], 0
	v_mov_b64_e32 v[112:113], 0
	v_mov_b64_e32 v[114:115], 0
	v_mov_b64_e32 v[116:117], 0
	v_mov_b64_e32 v[126:127], 0
	v_mov_b64_e32 v[128:129], 0
	v_mov_b64_e32 v[130:131], 0
	v_mov_b64_e32 v[132:133], 0

.LBB0_643:
	s_ashr_i32 s11, s10, 31
	s_lshl_b64 s[12:13], s[10:11], 19
	s_add_u32 s12, s26, s12
	s_addc_u32 s13, s27, s13
	s_and_b64 s[14:15], s[2:3], exec
	s_cselect_b32 s11, s13, s21
	s_cselect_b32 s17, s12, s20
	s_ashr_i32 s9, s8, 31
	s_lshl_b64 s[14:15], s[8:9], 19
	s_add_u32 s14, s28, s14
	s_addc_u32 s15, s29, s15
	s_and_b64 s[24:25], s[2:3], exec
	s_cselect_b32 s9, s15, s23
	s_cselect_b32 s41, s14, s22
	s_add_u32 s20, s20, 0x40080
	s_addc_u32 s21, s21, 0
	s_add_u32 s42, s22, 0x100
	v_mov_b32_e32 v6, 0
	s_addc_u32 s43, s23, 0
	s_mov_b32 s44, -2
	v_mov_b32_e32 v7, v6
	v_mov_b64_e32 v[8:9], 0
	v_mov_b64_e32 v[10:11], 0
	v_mov_b64_e32 v[12:13], 0
	v_mov_b64_e32 v[18:19], 0
	v_mov_b64_e32 v[20:21], 0
	v_mov_b64_e32 v[26:27], 0
	v_mov_b64_e32 v[28:29], 0
	v_mov_b64_e32 v[34:35], 0
	v_mov_b64_e32 v[36:37], 0
	v_mov_b64_e32 v[42:43], 0
	v_mov_b64_e32 v[44:45], 0
	v_mov_b64_e32 v[50:51], 0
	v_mov_b64_e32 v[52:53], 0
	v_mov_b64_e32 v[58:59], 0
	v_mov_b64_e32 v[60:61], 0
	v_mov_b64_e32 v[14:15], 0
	v_mov_b64_e32 v[16:17], 0
	v_mov_b64_e32 v[22:23], 0
	v_mov_b64_e32 v[24:25], 0
	v_mov_b64_e32 v[30:31], 0
	v_mov_b64_e32 v[32:33], 0
	v_mov_b64_e32 v[38:39], 0
	v_mov_b64_e32 v[40:41], 0
	v_mov_b64_e32 v[46:47], 0
	v_mov_b64_e32 v[48:49], 0
	v_mov_b64_e32 v[54:55], 0
	v_mov_b64_e32 v[56:57], 0
	v_mov_b64_e32 v[62:63], 0
	v_mov_b64_e32 v[64:65], 0
	v_mov_b64_e32 v[66:67], 0
	v_mov_b64_e32 v[68:69], 0
	v_mov_b64_e32 v[70:71], 0
	v_mov_b64_e32 v[72:73], 0
	v_mov_b64_e32 v[74:75], 0
	v_mov_b64_e32 v[76:77], 0
	v_mov_b64_e32 v[82:83], 0
	v_mov_b64_e32 v[84:85], 0
	v_mov_b64_e32 v[90:91], 0
	v_mov_b64_e32 v[92:93], 0
	v_mov_b64_e32 v[98:99], 0
	v_mov_b64_e32 v[100:101], 0
	v_mov_b64_e32 v[106:107], 0
	v_mov_b64_e32 v[108:109], 0
	v_mov_b64_e32 v[114:115], 0
	v_mov_b64_e32 v[116:117], 0
	v_mov_b64_e32 v[122:123], 0
	v_mov_b64_e32 v[124:125], 0
	v_mov_b64_e32 v[78:79], 0
	v_mov_b64_e32 v[80:81], 0
	v_mov_b64_e32 v[86:87], 0
	v_mov_b64_e32 v[88:89], 0
	v_mov_b64_e32 v[94:95], 0
	v_mov_b64_e32 v[96:97], 0
	v_mov_b64_e32 v[102:103], 0
	v_mov_b64_e32 v[104:105], 0
	v_mov_b64_e32 v[110:111], 0
	v_mov_b64_e32 v[112:113], 0
	v_mov_b64_e32 v[118:119], 0
	v_mov_b64_e32 v[120:121], 0
	v_mov_b64_e32 v[126:127], 0
	v_mov_b64_e32 v[128:129], 0
	v_mov_b64_e32 v[130:131], 0
	v_mov_b64_e32 v[132:133], 0
